# v22 + static s_setprio 1 for waves 0-3 (older half) during the attention phase, reset at phase end
# speedup vs baseline: 1.0087x; 1.0087x over previous
; #define LAS __attribute__((address_space(3)))
; __device__ __forceinline__ Frame fresh(const Frame& F0) { Frame F = F0; int t = threadIdx.x; asm volatile("" : "+v"(t)); F.tid = t; F.lane = t & 63; F.wave = __builtin_amdgcn_readfirstlane(t >> 6); return F; }
; __device__ __forceinline__ void fx_phase_attn(const Args& A, Frame& F0) {
;     Frame F = fresh(F0);
;     float qkmax;
;     { const float gq = wave_max(fabsf(A.fx_qn_g[F.lane])), gk = wave_max(fabsf(A.fx_kn_g[F.lane])); qkmax = 8.0f * 8.0f * 0.125f * LOG2E * gq * gk * 1.02f + 0.5f; }
;     unsigned* qctr = (unsigned*)(A.ws + WS_BAR) + 4096;
;     volatile LAS unsigned* slot = (volatile LAS unsigned*)(F.lds + 73728 + 8192);
;     for (;;) {
;         if (F.tid == 0) slot[0] = __hip_atomic_fetch_add(qctr, 1u, __ATOMIC_RELAXED, __HIP_MEMORY_SCOPE_AGENT);
;         __syncthreads();
;         const unsigned i = slot[0];
;         __syncthreads();
;         if (i >= 2048u) break;
;         fx_attn_unit(A, F, (int)(i & 63u), 31 - (int)(i >> 6), qkmax);
.LBB0_671:
	s_or_b64 exec, exec, s[4:5]
	v_mov_b32_e32 v2, v182
	s_waitcnt lgkmcnt(0)
	s_barrier
	v_readlane_b32 s4, v253, 5
	v_and_b32_e32 v110, 63, v2
	v_lshlrev_b32_e32 v0, 2, v110
	v_readlane_b32 s18, v253, 19
	v_readlane_b32 s19, v253, 20
	v_cmp_lt_i32_e32 vcc, v192, v186
	v_readfirstlane_b32 s0, v2
	s_ashr_i32 s1, s0, 6
	s_cmp_ge_u32 s1, 4
	s_cbranch_scc1 .Lattn_prio_done
	s_setprio 1
